# P0: x->bf16 conversion loop keeps 8 independent 16-byte loads in flight per lane (was one load + vmcnt(0) per iteration)
# speedup vs baseline: 1.0067x; 1.0067x over previous
; __device__ __forceinline__ u32x2 pack4(f32x4 v) { u32x2 r; r.x = cvt_pk_bf16(v.x, v.y); r.y = cvt_pk_bf16(v.z, v.w); return r; }
; template <int ph>
; __device__ __forceinline__ void run_phase(const Args& args, LAS unsigned char* lds, const int G, const int bx, const bool fin = true) {
;     ...
;         for (int i = gt; i < MT * D / 4; i += ngt) { const f32x4 v = (i < MP * D / 4) ? ((const f32x4*)x_prompt)[i] : ((const f32x4*)x_sample)[i - MP * D / 4];
;             ((u32x2*)HB)[i] = pack4(v); }
.LBB0_85:
	s_mov_b64 s[22:23], exec
	s_add_u32 s16, s34, 0x3c00000
	s_addc_u32 s17, s35, 0
	s_lshl_b32 s24, s2, 3
	v_mov_b32_e32 v12, v6
	v_mov_b32_e32 v13, 0
	v_mov_b32_e32 v15, 0
	v_mov_b32_e32 v17, 0
	v_mov_b32_e32 v19, 0
	v_mov_b32_e32 v21, 0
	v_mov_b32_e32 v23, 0
	v_mov_b32_e32 v25, 0
	v_mov_b32_e32 v27, 0
	v_mov_b32_e32 v61, 0
.Lx8_loop:
	v_add_u32_e32 v14, s2, v12
	v_add_u32_e32 v16, s2, v14
	v_add_u32_e32 v18, s2, v16
	v_add_u32_e32 v20, s2, v18
	v_add_u32_e32 v22, s2, v20
	v_add_u32_e32 v24, s2, v22
	v_add_u32_e32 v26, s2, v24
	v_min_u32_e32 v60, s10, v12
	v_cmp_gt_u32_e64 s[0:1], s3, v60
	v_lshl_add_u64 v[62:63], v[60:61], 4, s[52:53]
	v_lshl_add_u64 v[64:65], v[60:61], 4, s[54:55]
	v_lshl_add_u64 v[64:65], v[64:65], 0, s[20:21]
	v_cndmask_b32_e64 v62, v64, v62, s[0:1]
	v_cndmask_b32_e64 v63, v65, v63, s[0:1]
	global_load_dwordx4 v[28:31], v[62:63], off
	v_min_u32_e32 v60, s10, v14
	v_cmp_gt_u32_e64 s[0:1], s3, v60
	v_lshl_add_u64 v[62:63], v[60:61], 4, s[52:53]
	v_lshl_add_u64 v[64:65], v[60:61], 4, s[54:55]
	v_lshl_add_u64 v[64:65], v[64:65], 0, s[20:21]
	v_cndmask_b32_e64 v62, v64, v62, s[0:1]
	v_cndmask_b32_e64 v63, v65, v63, s[0:1]
	global_load_dwordx4 v[32:35], v[62:63], off
	v_min_u32_e32 v60, s10, v16
	v_cmp_gt_u32_e64 s[0:1], s3, v60
	v_lshl_add_u64 v[62:63], v[60:61], 4, s[52:53]
	v_lshl_add_u64 v[64:65], v[60:61], 4, s[54:55]
	v_lshl_add_u64 v[64:65], v[64:65], 0, s[20:21]
	v_cndmask_b32_e64 v62, v64, v62, s[0:1]
	v_cndmask_b32_e64 v63, v65, v63, s[0:1]
	global_load_dwordx4 v[36:39], v[62:63], off
	v_min_u32_e32 v60, s10, v18
	v_cmp_gt_u32_e64 s[0:1], s3, v60
	v_lshl_add_u64 v[62:63], v[60:61], 4, s[52:53]
	v_lshl_add_u64 v[64:65], v[60:61], 4, s[54:55]
	v_lshl_add_u64 v[64:65], v[64:65], 0, s[20:21]
	v_cndmask_b32_e64 v62, v64, v62, s[0:1]
	v_cndmask_b32_e64 v63, v65, v63, s[0:1]
	global_load_dwordx4 v[40:43], v[62:63], off
	v_min_u32_e32 v60, s10, v20
	v_cmp_gt_u32_e64 s[0:1], s3, v60
	v_lshl_add_u64 v[62:63], v[60:61], 4, s[52:53]
	v_lshl_add_u64 v[64:65], v[60:61], 4, s[54:55]
	v_lshl_add_u64 v[64:65], v[64:65], 0, s[20:21]
	v_cndmask_b32_e64 v62, v64, v62, s[0:1]
	v_cndmask_b32_e64 v63, v65, v63, s[0:1]
	global_load_dwordx4 v[44:47], v[62:63], off
	v_min_u32_e32 v60, s10, v22
	v_cmp_gt_u32_e64 s[0:1], s3, v60
	v_lshl_add_u64 v[62:63], v[60:61], 4, s[52:53]
	v_lshl_add_u64 v[64:65], v[60:61], 4, s[54:55]
	v_lshl_add_u64 v[64:65], v[64:65], 0, s[20:21]
	v_cndmask_b32_e64 v62, v64, v62, s[0:1]
	v_cndmask_b32_e64 v63, v65, v63, s[0:1]
	global_load_dwordx4 v[48:51], v[62:63], off
	v_min_u32_e32 v60, s10, v24
	v_cmp_gt_u32_e64 s[0:1], s3, v60
	v_lshl_add_u64 v[62:63], v[60:61], 4, s[52:53]
	v_lshl_add_u64 v[64:65], v[60:61], 4, s[54:55]
	v_lshl_add_u64 v[64:65], v[64:65], 0, s[20:21]
	v_cndmask_b32_e64 v62, v64, v62, s[0:1]
	v_cndmask_b32_e64 v63, v65, v63, s[0:1]
	global_load_dwordx4 v[52:55], v[62:63], off
	v_min_u32_e32 v60, s10, v26
	v_cmp_gt_u32_e64 s[0:1], s3, v60
	v_lshl_add_u64 v[62:63], v[60:61], 4, s[52:53]
	v_lshl_add_u64 v[64:65], v[60:61], 4, s[54:55]
	v_lshl_add_u64 v[64:65], v[64:65], 0, s[20:21]
	v_cndmask_b32_e64 v62, v64, v62, s[0:1]
	v_cndmask_b32_e64 v63, v65, v63, s[0:1]
	global_load_dwordx4 v[56:59], v[62:63], off
	s_waitcnt vmcnt(7)
	v_cvt_pk_bf16_f32 v28, v28, v29
	v_cvt_pk_bf16_f32 v29, v30, v31
	v_cmp_ge_u32_e64 s[0:1], s10, v12
	v_lshl_add_u64 v[62:63], v[12:13], 3, s[16:17]
	s_and_b64 exec, s[22:23], s[0:1]
	global_store_dwordx2 v[62:63], v[28:29], off
	s_mov_b64 exec, s[22:23]
	s_waitcnt vmcnt(7)
	v_cvt_pk_bf16_f32 v32, v32, v33
	v_cvt_pk_bf16_f32 v33, v34, v35
	v_cmp_ge_u32_e64 s[0:1], s10, v14
	v_lshl_add_u64 v[62:63], v[14:15], 3, s[16:17]
	s_and_b64 exec, s[22:23], s[0:1]
	global_store_dwordx2 v[62:63], v[32:33], off
	s_mov_b64 exec, s[22:23]
	s_waitcnt vmcnt(7)
	v_cvt_pk_bf16_f32 v36, v36, v37
	v_cvt_pk_bf16_f32 v37, v38, v39
	v_cmp_ge_u32_e64 s[0:1], s10, v16
	v_lshl_add_u64 v[62:63], v[16:17], 3, s[16:17]
	s_and_b64 exec, s[22:23], s[0:1]
	global_store_dwordx2 v[62:63], v[36:37], off
	s_mov_b64 exec, s[22:23]
	s_waitcnt vmcnt(7)
	v_cvt_pk_bf16_f32 v40, v40, v41
	v_cvt_pk_bf16_f32 v41, v42, v43
	v_cmp_ge_u32_e64 s[0:1], s10, v18
	v_lshl_add_u64 v[62:63], v[18:19], 3, s[16:17]
	s_and_b64 exec, s[22:23], s[0:1]
	global_store_dwordx2 v[62:63], v[40:41], off
	s_mov_b64 exec, s[22:23]
	s_waitcnt vmcnt(7)
	v_cvt_pk_bf16_f32 v44, v44, v45
	v_cvt_pk_bf16_f32 v45, v46, v47
	v_cmp_ge_u32_e64 s[0:1], s10, v20
	v_lshl_add_u64 v[62:63], v[20:21], 3, s[16:17]
	s_and_b64 exec, s[22:23], s[0:1]
	global_store_dwordx2 v[62:63], v[44:45], off
	s_mov_b64 exec, s[22:23]
	s_waitcnt vmcnt(7)
	v_cvt_pk_bf16_f32 v48, v48, v49
	v_cvt_pk_bf16_f32 v49, v50, v51
	v_cmp_ge_u32_e64 s[0:1], s10, v22
	v_lshl_add_u64 v[62:63], v[22:23], 3, s[16:17]
	s_and_b64 exec, s[22:23], s[0:1]
	global_store_dwordx2 v[62:63], v[48:49], off
	s_mov_b64 exec, s[22:23]
	s_waitcnt vmcnt(7)
	v_cvt_pk_bf16_f32 v52, v52, v53
	v_cvt_pk_bf16_f32 v53, v54, v55
	v_cmp_ge_u32_e64 s[0:1], s10, v24
	v_lshl_add_u64 v[62:63], v[24:25], 3, s[16:17]
	s_and_b64 exec, s[22:23], s[0:1]
	global_store_dwordx2 v[62:63], v[52:53], off
	s_mov_b64 exec, s[22:23]
	s_waitcnt vmcnt(7)
	v_cvt_pk_bf16_f32 v56, v56, v57
	v_cvt_pk_bf16_f32 v57, v58, v59
	v_cmp_ge_u32_e64 s[0:1], s10, v26
	v_lshl_add_u64 v[62:63], v[26:27], 3, s[16:17]
	s_and_b64 exec, s[22:23], s[0:1]
	global_store_dwordx2 v[62:63], v[56:57], off
	s_mov_b64 exec, s[22:23]
	v_add_u32_e32 v12, s24, v12
	v_cmp_ge_u32_e64 s[0:1], s10, v12
	s_nop 1
	s_and_b64 s[22:23], s[22:23], s[0:1]
	s_mov_b64 exec, s[22:23]
	s_cbranch_execnz .Lx8_loop
